# hoist loop-invariant RMSNorm gain loads out of P0 and P11 row loops (removes 7 serialized load+vmcnt(0) per iteration)
# baseline (speedup 1.0000x reference)
; template <bool OUT_BF16> __device__ __forceinline__ void rms_rows(const float* X, const float* gain, void* out, int gw, int ngw, int lane) {
;     int m = gw;
;     for (; m + ngw < M; m += 2 * ngw) {
;         const f32x4* xr0 = (const f32x4*)(X + (size_t)m * D) + lane; const f32x4* xr1 = (const f32x4*)(X + (size_t)(m + ngw) * D) + lane;
;         f32x4 v0[8], v1[8]; float s0 = 0.f, s1 = 0.f;
; #pragma unroll
;         for (int j = 0; j < 8; ++j) { v0[j] = xr0[64 * j]; v1[j] = xr1[64 * j]; }
.LBB0_48:
	s_or_b64 exec, exec, s[0:1]
	v_readlane_b32 s0, v254, 42
	s_add_i32 s0, s68, s0
	v_readlane_b32 s34, v255, 2
	s_cmpk_gt_i32 s0, 0x3fff
	v_lshlrev_b32_e32 v64, 3, v188
	s_mov_b32 s4, s68
	v_readlane_b32 s35, v255, 3
	v_readlane_b32 s1, v254, 43
	s_cbranch_scc1 .LBB0_52
	v_mbcnt_lo_u32_b32 v2, -1, 0
	v_mbcnt_hi_u32_b32 v2, -1, v2
	v_and_b32_e32 v3, 64, v2
	v_add_u32_e32 v3, 64, v3
	v_xor_b32_e32 v4, 1, v2
	v_cmp_lt_i32_e32 vcc, v4, v3
	v_lshlrev_b32_e32 v0, 4, v188
	v_mov_b32_e32 v1, 0
	v_cndmask_b32_e32 v4, v2, v4, vcc
	v_lshlrev_b32_e32 v87, 2, v4
	v_xor_b32_e32 v4, 2, v2
	v_cmp_lt_i32_e32 vcc, v4, v3
	v_readlane_b32 s8, v254, 7
	v_readlane_b32 s4, v254, 44
	v_cndmask_b32_e32 v4, v2, v4, vcc
	v_lshlrev_b32_e32 v88, 2, v4
	v_xor_b32_e32 v4, 4, v2
	v_cmp_lt_i32_e32 vcc, v4, v3
	v_readlane_b32 s10, v254, 9
	v_readlane_b32 s11, v254, 10
	v_cndmask_b32_e32 v4, v2, v4, vcc
	v_lshlrev_b32_e32 v89, 2, v4
	v_xor_b32_e32 v4, 8, v2
	v_cmp_lt_i32_e32 vcc, v4, v3
	v_mov_b32_e32 v65, v1
	v_readlane_b32 s5, v254, 45
	v_cndmask_b32_e32 v4, v2, v4, vcc
	v_lshlrev_b32_e32 v90, 2, v4
	v_xor_b32_e32 v4, 16, v2
	v_cmp_lt_i32_e32 vcc, v4, v3
	s_add_i32 s1, s66, s67
	s_ashr_i32 s69, s68, 31
	v_cndmask_b32_e32 v4, v2, v4, vcc
	v_lshlrev_b32_e32 v91, 2, v4
	v_xor_b32_e32 v4, 32, v2
	v_cmp_lt_i32_e32 vcc, v4, v3
	v_mov_b32_e32 v3, v1
	s_lshl_b32 s26, s67, 4
	v_cndmask_b32_e32 v2, v2, v4, vcc
	v_lshlrev_b32_e32 v92, 2, v2
	v_or_b32_e32 v2, 0x1000, v0
	v_lshl_add_u64 v[70:71], s[10:11], 0, v[2:3]
	v_or_b32_e32 v2, 0x1400, v0
	v_lshl_add_u64 v[78:79], s[4:5], 0, v[64:65]
	s_lshl_b32 s3, s1, 3
	s_lshl_b64 s[4:5], s[68:69], 12
	v_lshl_add_u64 v[72:73], s[10:11], 0, v[2:3]
	v_or_b32_e32 v2, 0x1800, v0
	s_add_u32 s4, s90, s4
	v_lshl_add_u64 v[74:75], s[10:11], 0, v[2:3]
	v_or_b32_e32 v2, 0x1c00, v0
	s_addc_u32 s5, s91, s5
	v_lshl_add_u64 v[76:77], s[10:11], 0, v[2:3]
	v_lshl_add_u64 v[2:3], s[4:5], 0, v[64:65]
	s_mov_b64 s[4:5], 0xb500000
	s_ashr_i32 s27, s26, 31
	v_lshl_add_u64 v[80:81], v[2:3], 0, s[4:5]
	s_lshl_b64 s[30:31], s[26:27], 12
	s_lshl_b64 s[4:5], s[68:69], 13
	v_readlane_b32 s9, v254, 8
	s_add_u32 s4, s8, s4
	s_addc_u32 s5, s9, s5
	v_lshl_add_u64 v[66:67], s[8:9], 0, v[0:1]
	v_lshl_add_u64 v[68:69], s[10:11], 0, v[0:1]
	v_lshl_add_u64 v[0:1], s[4:5], 0, v[0:1]
	s_mov_b64 s[4:5], 0x1000
	s_movk_i32 s2, 0x1000
	v_lshl_add_u64 v[82:83], v[0:1], 0, s[4:5]
	s_lshl_b64 s[40:41], s[26:27], 13
	v_mov_b32_e32 v65, 0x358637bd
	s_mov_b32 s8, 0xf800000
	v_mov_b32_e32 v93, 0x260
	v_readlane_b32 s9, v254, 40
	s_mov_b32 s10, s68
	v_readlane_b32 s6, v254, 42
	v_readlane_b32 s12, v254, 11
	v_readlane_b32 s13, v254, 12
	v_readlane_b32 s14, v254, 13
	v_readlane_b32 s15, v254, 14
	v_readlane_b32 s16, v254, 15
	v_readlane_b32 s17, v254, 16
	v_readlane_b32 s18, v254, 17
	v_readlane_b32 s19, v254, 18
	v_readlane_b32 s20, v254, 19
	v_readlane_b32 s21, v254, 20
	v_readlane_b32 s22, v254, 21
	v_readlane_b32 s23, v254, 22
	v_readlane_b32 s7, v254, 43
	global_load_dwordx4 v[140:143], v[68:69], off offset:1024
	global_load_dwordx4 v[144:147], v[68:69], off offset:2048
	global_load_dwordx4 v[148:151], v[68:69], off offset:3072
	global_load_dwordx4 v[152:155], v[70:71], off
	global_load_dwordx4 v[156:159], v[72:73], off
	global_load_dwordx4 v[160:163], v[74:75], off
	global_load_dwordx4 v[164:167], v[76:77], off
.LBB0_50:
	global_load_dwordx4 v[28:31], v[82:83], off offset:-4096
	global_load_dwordx4 v[24:27], v[82:83], off offset:-3072
	global_load_dwordx4 v[20:23], v[82:83], off offset:-2048
	global_load_dwordx4 v[12:15], v[82:83], off
	global_load_dwordx4 v[16:19], v[82:83], off offset:-1024
	global_load_dwordx4 v[8:11], v[82:83], off offset:1024
	global_load_dwordx4 v[0:3], v[82:83], off offset:3072
	global_load_dwordx4 v[4:7], v[82:83], off offset:2048
	s_ashr_i32 s1, s0, 31
	s_lshl_b64 s[4:5], s[0:1], 13
	v_lshl_add_u64 v[32:33], v[66:67], 0, s[4:5]
	global_load_dwordx4 v[60:63], v[68:69], off
	global_load_dwordx4 v[94:97], v[32:33], off
	global_load_dwordx4 v[56:59], v[32:33], off offset:1024
	global_load_dwordx4 v[52:55], v[32:33], off offset:2048
	global_load_dwordx4 v[48:51], v[32:33], off offset:3072
	v_add_co_u32_e32 v36, vcc, s2, v32
	s_lshl_b64 s[0:1], s[0:1], 12
	s_nop 0
	v_addc_co_u32_e32 v37, vcc, 0, v33, vcc
	global_load_dwordx4 v[44:47], v[36:37], off
	global_load_dwordx4 v[40:43], v[36:37], off offset:1024
	global_load_dwordx4 v[32:35], v[36:37], off offset:3072
	s_nop 0
	global_load_dwordx4 v[36:39], v[36:37], off offset:2048
	v_lshl_add_u64 v[84:85], v[78:79], 0, s[0:1]
	s_add_i32 s10, s10, s26
	s_add_i32 s9, s9, s26
	v_lshl_add_u64 v[82:83], v[82:83], 0, s[40:41]
	s_waitcnt vmcnt(16)
	v_mov_b32_e32 v100, v29
	s_waitcnt vmcnt(15)
	v_mov_b32_e32 v101, v25
	v_mov_b32_e32 v104, v31
	v_mov_b32_e32 v105, v27
	v_mov_b32_e32 v98, v28
	v_mov_b32_e32 v99, v24
	v_mov_b32_e32 v102, v30
	v_mov_b32_e32 v103, v26
	s_waitcnt vmcnt(14)
	v_pk_mul_f32 v[106:107], v[22:23], v[22:23]
	v_pk_mul_f32 v[108:109], v[20:21], v[20:21]
	v_pk_mul_f32 v[100:101], v[100:101], v[100:101]
	v_pk_mul_f32 v[104:105], v[104:105], v[104:105]
	s_waitcnt vmcnt(13)
	v_mul_f32_e32 v119, v14, v14
	s_waitcnt vmcnt(12)
	v_mul_f32_e32 v86, v17, v17
	s_waitcnt vmcnt(11)
	v_pk_mul_f32 v[112:113], v[10:11], v[10:11]
	v_pk_mul_f32 v[114:115], v[8:9], v[8:9]
	s_waitcnt vmcnt(9)
; __device__ __forceinline__ float wave_sum(float v) {
; #pragma unroll
;     for (int o = 1; o < 64; o <<= 1) v += __shfl_xor(v, o);
;     return v;
; }
; template <bool OUT_BF16> __device__ __forceinline__ void rms_rows(const float* X, const float* gain, void* out, int gw, int ngw, int lane) {
;     ...
;         for (int j = 0; j < 8; ++j) { s0 += (v0[j].x * v0[j].x + v0[j].y * v0[j].y) + (v0[j].z * v0[j].z + v0[j].w * v0[j].w); s1 += (v1[j].x * v1[j].x + v1[j].y * v1[j].y) + (v1[j].z * v1[j].z + v1[j].w * v1[j].w); }
;         const float rs0 = 1.0f / sqrtf(wave_sum(s0) * (1.0f / D) + EPS), rs1 = 1.0f / sqrtf(wave_sum(s1) * (1.0f / D) + EPS);
	v_mul_f32_e32 v116, v5, v5
	v_mul_f32_e32 v118, v7, v7
	v_pk_mov_b32 v[120:121], v[108:109], v[106:107] op_sel:[1,0]
	v_mov_b32_e32 v109, v107
	v_pk_fma_f32 v[98:99], v[98:99], v[98:99], v[100:101]
	v_pk_fma_f32 v[100:101], v[102:103], v[102:103], v[104:105]
	v_mul_f32_e32 v110, v19, v19
	v_mul_f32_e32 v126, v2, v2
	v_mul_f32_e32 v127, v3, v3
	v_pk_fma_f32 v[106:107], v[16:17], v[16:17], v[86:87] op_sel_hi:[1,1,0]
	v_pk_mov_b32 v[122:123], v[114:115], v[112:113] op_sel:[1,0]
	v_mov_b32_e32 v115, v113
	v_pk_fma_f32 v[112:113], v[4:5], v[4:5], v[116:117] op_sel_hi:[1,1,0]
	v_pk_fma_f32 v[116:117], v[6:7], v[6:7], v[118:119] op_sel_hi:[1,1,0]
	v_pk_add_f32 v[102:103], v[120:121], v[108:109]
	v_pk_add_f32 v[98:99], v[98:99], v[100:101]
	v_mul_f32_e32 v129, v12, v12
	v_mul_f32_e32 v124, v13, v13
	v_mul_f32_e32 v125, v15, v15
	v_pk_fma_f32 v[110:111], v[18:19], v[18:19], v[110:111] op_sel_hi:[1,1,0]
	v_mov_b32_e32 v107, v119
	v_mov_b32_e32 v113, v126
	v_mov_b32_e32 v117, v127
	s_waitcnt vmcnt(7)
	v_mov_b32_e32 v108, v95
	s_waitcnt vmcnt(6)
	v_mov_b32_e32 v109, v57
	v_mov_b32_e32 v118, v97
	v_mov_b32_e32 v119, v59
	v_pk_add_f32 v[102:103], v[102:103], v[102:103] op_sel:[0,1] op_sel_hi:[1,0]
	v_pk_add_f32 v[98:99], v[98:99], v[98:99] op_sel:[0,1] op_sel_hi:[1,0]
	v_mov_b32_e32 v111, v125
	v_pk_add_f32 v[104:105], v[122:123], v[114:115]
	v_mov_b32_e32 v100, v94
	v_mov_b32_e32 v101, v56
	v_mov_b32_e32 v114, v96
	v_mov_b32_e32 v115, v58
	s_waitcnt vmcnt(5)
	v_pk_mul_f32 v[120:121], v[54:55], v[54:55]
	v_pk_mul_f32 v[122:123], v[52:53], v[52:53]
	v_pk_add_f32 v[112:113], v[112:113], v[116:117]
	v_pk_mul_f32 v[108:109], v[108:109], v[108:109]
	v_pk_mul_f32 v[116:117], v[118:119], v[118:119]
	v_mov_b32_e32 v103, v124
	v_mov_b32_e32 v99, v129
	v_pk_add_f32 v[106:107], v[106:107], v[110:111]
	v_pk_mov_b32 v[118:119], v[122:123], v[120:121] op_sel:[1,0]
	v_mov_b32_e32 v123, v121
	v_pk_fma_f32 v[100:101], v[100:101], v[100:101], v[108:109]
	v_pk_fma_f32 v[108:109], v[114:115], v[114:115], v[116:117]
	v_pk_add_f32 v[98:99], v[98:99], v[102:103]
	s_waitcnt vmcnt(4)
	v_mul_f32_e32 v86, v49, v49
	v_mul_f32_e32 v110, v51, v51
	v_pk_add_f32 v[114:115], v[118:119], v[122:123]
	v_pk_add_f32 v[100:101], v[100:101], v[108:109]
	v_pk_add_f32 v[98:99], v[98:99], v[106:107]
	v_mul_f32_e32 v130, v0, v0
	v_mul_f32_e32 v128, v1, v1
	v_pk_add_f32 v[104:105], v[104:105], v[104:105] op_sel:[0,1] op_sel_hi:[1,0]
	s_waitcnt vmcnt(3)
	v_mul_f32_e32 v131, v44, v44
	v_mul_f32_e32 v132, v45, v45
	v_mul_f32_e32 v133, v46, v46
	v_mul_f32_e32 v134, v47, v47
	v_pk_fma_f32 v[120:121], v[48:49], v[48:49], v[86:87] op_sel_hi:[1,1,0]
	v_pk_fma_f32 v[110:111], v[50:51], v[50:51], v[110:111] op_sel_hi:[1,1,0]
	v_pk_add_f32 v[102:103], v[114:115], v[114:115] op_sel:[0,1] op_sel_hi:[1,0]
	v_pk_add_f32 v[100:101], v[100:101], v[100:101] op_sel:[0,1] op_sel_hi:[1,0]
	v_pk_add_f32 v[98:99], v[98:99], v[98:99] op_sel:[0,1] op_sel_hi:[1,0]
	s_waitcnt vmcnt(2)
	v_pk_mul_f32 v[124:125], v[42:43], v[42:43]
	v_pk_mul_f32 v[126:127], v[40:41], v[40:41]
	v_mov_b32_e32 v105, v128
	v_mov_b32_e32 v121, v133
	v_mov_b32_e32 v111, v134
	v_mov_b32_e32 v103, v132
	v_mov_b32_e32 v101, v131
	v_mov_b32_e32 v99, v130
	v_pk_mov_b32 v[116:117], v[126:127], v[124:125] op_sel:[1,0]
	v_mov_b32_e32 v127, v125
	v_pk_add_f32 v[108:109], v[120:121], v[110:111]
	v_pk_add_f32 v[100:101], v[100:101], v[102:103]
	v_pk_add_f32 v[98:99], v[98:99], v[104:105]
	s_waitcnt vmcnt(0)
	v_mul_f32_e32 v86, v37, v37
	v_mul_f32_e32 v128, v39, v39
	v_pk_add_f32 v[110:111], v[116:117], v[126:127]
	v_pk_add_f32 v[100:101], v[100:101], v[108:109]
	v_pk_add_f32 v[98:99], v[98:99], v[112:113]
	v_mul_f32_e32 v135, v32, v32
	v_mul_f32_e32 v136, v33, v33
	v_mul_f32_e32 v137, v34, v34
	v_mul_f32_e32 v138, v35, v35
	v_pk_fma_f32 v[118:119], v[36:37], v[36:37], v[86:87] op_sel_hi:[1,1,0]
	v_pk_fma_f32 v[122:123], v[38:39], v[38:39], v[128:129] op_sel_hi:[1,1,0]
	v_pk_add_f32 v[106:107], v[110:111], v[110:111] op_sel:[0,1] op_sel_hi:[1,0]
	v_pk_add_f32 v[100:101], v[100:101], v[100:101] op_sel:[0,1] op_sel_hi:[1,0]
	v_add_f32_e32 v86, v98, v99
	v_mov_b32_e32 v119, v137
	v_mov_b32_e32 v123, v138
	v_mov_b32_e32 v107, v136
	v_mov_b32_e32 v101, v135
	ds_bpermute_b32 v102, v87, v86
	v_pk_add_f32 v[110:111], v[118:119], v[122:123]
	v_pk_add_f32 v[98:99], v[100:101], v[106:107]
	s_waitcnt lgkmcnt(0)
	v_add_f32_e32 v86, v86, v102
	v_pk_add_f32 v[98:99], v[98:99], v[110:111]
	ds_bpermute_b32 v100, v88, v86
	v_add_f32_e32 v98, v98, v99
	ds_bpermute_b32 v99, v87, v98
	s_waitcnt lgkmcnt(1)
	v_add_f32_e32 v86, v86, v100
	ds_bpermute_b32 v100, v89, v86
	s_waitcnt lgkmcnt(1)
	v_add_f32_e32 v98, v98, v99
	ds_bpermute_b32 v99, v88, v98
	s_waitcnt lgkmcnt(1)
	v_add_f32_e32 v86, v86, v100
	ds_bpermute_b32 v100, v90, v86
	s_waitcnt lgkmcnt(1)
	v_add_f32_e32 v98, v98, v99
	ds_bpermute_b32 v99, v89, v98
	s_waitcnt lgkmcnt(1)
	v_add_f32_e32 v86, v86, v100
	ds_bpermute_b32 v100, v91, v86
	s_waitcnt lgkmcnt(1)
	v_add_f32_e32 v98, v98, v99
	ds_bpermute_b32 v99, v90, v98
	s_waitcnt lgkmcnt(1)
	v_add_f32_e32 v86, v86, v100
	ds_bpermute_b32 v100, v92, v86
	s_waitcnt lgkmcnt(1)
	v_add_f32_e32 v98, v98, v99
	ds_bpermute_b32 v99, v91, v98
	s_waitcnt lgkmcnt(1)
	v_add_f32_e32 v86, v86, v100
	v_fmamk_f32 v86, v86, 0x3a000000, v65
	s_waitcnt lgkmcnt(0)
	v_add_f32_e32 v98, v98, v99
	ds_bpermute_b32 v99, v92, v98
	v_mul_f32_e32 v100, 0x4f800000, v86
	v_cmp_gt_f32_e32 vcc, s8, v86
	s_waitcnt lgkmcnt(0)
; __device__ __forceinline__ unsigned pk2(float lo, float hi) { typedef float f2_t __attribute__((ext_vector_type(2))); typedef __bf16 b2_t __attribute__((ext_vector_type(2))); const f2_t v = {lo, hi}; return __builtin_bit_cast(unsigned, __builtin_convertvector(v, b2_t)); }
; template <bool OUT_BF16> __device__ __forceinline__ void rms_rows(const float* X, const float* gain, void* out, int gw, int ngw, int lane) {
;     ...
;         const float rs0 = 1.0f / sqrtf(wave_sum(s0) * (1.0f / D) + EPS), rs1 = 1.0f / sqrtf(wave_sum(s1) * (1.0f / D) + EPS);
; #pragma unroll
;         for (int j = 0; j < 8; ++j) {
;             const f32x4 g = ((const f32x4*)gain)[lane + 64 * j]; const f32x4 o0 = v0[j] * rs0 * g, o1 = v1[j] * rs1 * g;
;             if (OUT_BF16) { v2u w0, w1; w0.x = pk2(o0.x, o0.y); w0.y = pk2(o0.z, o0.w); w1.x = pk2(o1.x, o1.y); w1.y = pk2(o1.z, o1.w);
;                 ((v2u*)((bf16*)out + (size_t)m * D))[lane + 64 * j] = w0; ((v2u*)((bf16*)out + (size_t)(m + ngw) * D))[lane + 64 * j] = w1; }
	v_add_f32_e32 v98, v98, v99
	v_cndmask_b32_e32 v86, v86, v100, vcc
	v_sqrt_f32_e32 v99, v86
	v_fmamk_f32 v98, v98, 0x3a000000, v65
	v_mul_f32_e32 v100, 0x4f800000, v98
	v_cmp_gt_f32_e64 s[0:1], s8, v98
	v_add_u32_e32 v101, -1, v99
	v_add_u32_e32 v102, 1, v99
	v_cndmask_b32_e64 v98, v98, v100, s[0:1]
	v_sqrt_f32_e32 v100, v98
	v_fma_f32 v103, -v101, v99, v86
	v_fma_f32 v104, -v102, v99, v86
	v_cmp_ge_f32_e64 s[4:5], 0, v103
	s_nop 1
	v_cndmask_b32_e64 v99, v99, v101, s[4:5]
	v_cmp_lt_f32_e64 s[4:5], 0, v104
	v_add_u32_e32 v101, -1, v100
	v_fma_f32 v104, -v101, v100, v98
	v_cndmask_b32_e64 v99, v99, v102, s[4:5]
	v_add_u32_e32 v102, 1, v100
	v_mul_f32_e32 v103, 0x37800000, v99
	v_fma_f32 v105, -v102, v100, v98
	v_cndmask_b32_e32 v99, v99, v103, vcc
	v_cmp_ge_f32_e32 vcc, 0, v104
	v_cmp_class_f32_e64 s[4:5], v86, v93
	s_nop 0
	v_cndmask_b32_e32 v100, v100, v101, vcc
	v_cmp_lt_f32_e32 vcc, 0, v105
	v_cndmask_b32_e64 v86, v99, v86, s[4:5]
	s_nop 0
	v_cndmask_b32_e32 v99, v100, v102, vcc
	v_div_scale_f32 v100, s[4:5], v86, v86, 1.0
	v_mul_f32_e32 v102, 0x37800000, v99
	v_rcp_f32_e32 v103, v100
	v_cndmask_b32_e64 v99, v99, v102, s[0:1]
	v_cmp_class_f32_e64 s[0:1], v98, v93
	v_div_scale_f32 v101, vcc, 1.0, v86, 1.0
	s_nop 0
	v_cndmask_b32_e64 v102, v99, v98, s[0:1]
	v_div_scale_f32 v98, s[0:1], v102, v102, 1.0
	v_rcp_f32_e32 v104, v98
	v_fma_f32 v105, -v100, v103, 1.0
	v_fmac_f32_e32 v103, v105, v103
	v_mul_f32_e32 v105, v101, v103
	v_fma_f32 v106, -v100, v105, v101
	v_fma_f32 v107, -v98, v104, 1.0
	v_div_scale_f32 v99, s[0:1], 1.0, v102, 1.0
	v_fmac_f32_e32 v105, v106, v103
	v_fmac_f32_e32 v104, v107, v104
	v_fma_f32 v100, -v100, v105, v101
	v_mul_f32_e32 v101, v99, v104
	v_div_fmas_f32 v100, v100, v103, v105
	v_fma_f32 v103, -v98, v101, v99
	v_fmac_f32_e32 v101, v103, v104
	v_div_fixup_f32 v86, v100, v86, 1.0
	v_fma_f32 v98, -v98, v101, v99
	s_mov_b64 vcc, s[0:1]
	v_pk_mul_f32 v[28:29], v[28:29], v[86:87] op_sel_hi:[1,0]
	v_pk_mul_f32 v[30:31], v[30:31], v[86:87] op_sel_hi:[1,0]
	v_div_fmas_f32 v100, v98, v104, v101
	v_pk_mul_f32 v[30:31], v[62:63], v[30:31]
	v_pk_mul_f32 v[98:99], v[60:61], v[28:29]
	v_div_fixup_f32 v28, v100, v102, 1.0
	v_cvt_pk_bf16_f32 v98, v98, v99
	v_cvt_pk_bf16_f32 v99, v30, v31
	v_pk_mul_f32 v[30:31], v[94:95], v[28:29] op_sel_hi:[1,0]
	v_pk_mul_f32 v[94:95], v[96:97], v[28:29] op_sel_hi:[1,0]
	v_pk_mul_f32 v[30:31], v[60:61], v[30:31]
	v_pk_mul_f32 v[62:63], v[62:63], v[94:95]
	v_cvt_pk_bf16_f32 v30, v30, v31
	v_cvt_pk_bf16_f32 v31, v62, v63
	global_store_dwordx2 v[80:81], v[98:99], off
	global_store_dwordx2 v[84:85], v[30:31], off
	s_nop 0
	v_pk_mul_f32 v[24:25], v[24:25], v[86:87] op_sel_hi:[1,0]
	v_pk_mul_f32 v[26:27], v[26:27], v[86:87] op_sel_hi:[1,0]
	v_pk_mul_f32 v[30:31], v[56:57], v[28:29] op_sel_hi:[1,0]
	v_pk_mul_f32 v[56:57], v[58:59], v[28:29] op_sel_hi:[1,0]
	v_pk_mul_f32 v[20:21], v[20:21], v[86:87] op_sel_hi:[1,0]
	v_pk_mul_f32 v[22:23], v[22:23], v[86:87] op_sel_hi:[1,0]
	v_pk_mul_f32 v[16:17], v[16:17], v[86:87] op_sel_hi:[1,0]
	v_pk_mul_f32 v[18:19], v[18:19], v[86:87] op_sel_hi:[1,0]
	v_pk_mul_f32 v[12:13], v[12:13], v[86:87] op_sel_hi:[1,0]
	v_pk_mul_f32 v[14:15], v[14:15], v[86:87] op_sel_hi:[1,0]
	v_pk_mul_f32 v[8:9], v[8:9], v[86:87] op_sel_hi:[1,0]
	v_pk_mul_f32 v[10:11], v[10:11], v[86:87] op_sel_hi:[1,0]
	v_pk_mul_f32 v[4:5], v[4:5], v[86:87] op_sel_hi:[1,0]
	v_pk_mul_f32 v[6:7], v[6:7], v[86:87] op_sel_hi:[1,0]
	v_pk_mul_f32 v[0:1], v[0:1], v[86:87] op_sel_hi:[1,0]
	v_pk_mul_f32 v[2:3], v[2:3], v[86:87] op_sel_hi:[1,0]
	s_add_i32 s0, s10, s6
	s_add_i32 s1, s3, s9
	s_cmpk_gt_i32 s1, 0x3fff
	s_nop 0
	v_pk_mul_f32 v[26:27], v[142:143], v[26:27]
	v_pk_mul_f32 v[24:25], v[140:141], v[24:25]
	v_pk_mul_f32 v[56:57], v[142:143], v[56:57]
; __device__ __forceinline__ unsigned pk2(float lo, float hi) { typedef float f2_t __attribute__((ext_vector_type(2))); typedef __bf16 b2_t __attribute__((ext_vector_type(2))); const f2_t v = {lo, hi}; return __builtin_bit_cast(unsigned, __builtin_convertvector(v, b2_t)); }
; template <bool OUT_BF16> __device__ __forceinline__ void rms_rows(const float* X, const float* gain, void* out, int gw, int ngw, int lane) {
;     ...
;         for (int j = 0; j < 8; ++j) {
;             const f32x4 g = ((const f32x4*)gain)[lane + 64 * j]; const f32x4 o0 = v0[j] * rs0 * g, o1 = v1[j] * rs1 * g;
;             if (OUT_BF16) { v2u w0, w1; w0.x = pk2(o0.x, o0.y); w0.y = pk2(o0.z, o0.w); w1.x = pk2(o1.x, o1.y); w1.y = pk2(o1.z, o1.w);
;                 ((v2u*)((bf16*)out + (size_t)m * D))[lane + 64 * j] = w0; ((v2u*)((bf16*)out + (size_t)(m + ngw) * D))[lane + 64 * j] = w1; }
	v_pk_mul_f32 v[30:31], v[140:141], v[30:31]
	v_cvt_pk_bf16_f32 v24, v24, v25
	v_cvt_pk_bf16_f32 v25, v26, v27
	v_cvt_pk_bf16_f32 v26, v30, v31
	v_cvt_pk_bf16_f32 v27, v56, v57
	global_store_dwordx2 v[80:81], v[24:25], off offset:512
	global_store_dwordx2 v[84:85], v[26:27], off offset:512
	s_nop 0
	v_pk_mul_f32 v[30:31], v[52:53], v[28:29] op_sel_hi:[1,0]
	v_pk_mul_f32 v[52:53], v[54:55], v[28:29] op_sel_hi:[1,0]
	s_nop 0
	v_pk_mul_f32 v[22:23], v[22:23], v[146:147]
	v_pk_mul_f32 v[20:21], v[20:21], v[144:145]
	v_pk_mul_f32 v[26:27], v[146:147], v[52:53]
	v_pk_mul_f32 v[24:25], v[144:145], v[30:31]
	v_cvt_pk_bf16_f32 v20, v20, v21
	v_cvt_pk_bf16_f32 v21, v22, v23
	v_cvt_pk_bf16_f32 v22, v24, v25
	v_cvt_pk_bf16_f32 v23, v26, v27
	global_store_dwordx2 v[80:81], v[20:21], off offset:1024
	global_store_dwordx2 v[84:85], v[22:23], off offset:1024
	s_nop 0
	v_pk_mul_f32 v[24:25], v[48:49], v[28:29] op_sel_hi:[1,0]
	v_pk_mul_f32 v[26:27], v[50:51], v[28:29] op_sel_hi:[1,0]
	s_nop 0
	v_pk_mul_f32 v[18:19], v[18:19], v[150:151]
	v_pk_mul_f32 v[16:17], v[16:17], v[148:149]
	v_pk_mul_f32 v[22:23], v[26:27], v[150:151]
	v_pk_mul_f32 v[20:21], v[24:25], v[148:149]
	v_cvt_pk_bf16_f32 v16, v16, v17
	v_cvt_pk_bf16_f32 v17, v18, v19
	v_cvt_pk_bf16_f32 v18, v20, v21
	v_cvt_pk_bf16_f32 v19, v22, v23
	global_store_dwordx2 v[80:81], v[16:17], off offset:1536
	global_store_dwordx2 v[84:85], v[18:19], off offset:1536
	s_nop 0
	v_pk_mul_f32 v[20:21], v[44:45], v[28:29] op_sel_hi:[1,0]
	v_pk_mul_f32 v[22:23], v[46:47], v[28:29] op_sel_hi:[1,0]
	s_nop 0
	v_pk_mul_f32 v[14:15], v[14:15], v[154:155]
	v_pk_mul_f32 v[12:13], v[12:13], v[152:153]
	v_pk_mul_f32 v[18:19], v[22:23], v[154:155]
	v_pk_mul_f32 v[16:17], v[20:21], v[152:153]
	v_cvt_pk_bf16_f32 v12, v12, v13
	v_cvt_pk_bf16_f32 v13, v14, v15
	v_cvt_pk_bf16_f32 v14, v16, v17
	v_cvt_pk_bf16_f32 v15, v18, v19
	global_store_dwordx2 v[80:81], v[12:13], off offset:2048
	global_store_dwordx2 v[84:85], v[14:15], off offset:2048
	s_nop 0
	v_pk_mul_f32 v[16:17], v[40:41], v[28:29] op_sel_hi:[1,0]
	v_pk_mul_f32 v[18:19], v[42:43], v[28:29] op_sel_hi:[1,0]
	s_nop 0
	v_pk_mul_f32 v[10:11], v[10:11], v[158:159]
	v_pk_mul_f32 v[8:9], v[8:9], v[156:157]
	v_pk_mul_f32 v[14:15], v[18:19], v[158:159]
	v_pk_mul_f32 v[12:13], v[16:17], v[156:157]
	v_cvt_pk_bf16_f32 v8, v8, v9
	v_cvt_pk_bf16_f32 v9, v10, v11
	v_cvt_pk_bf16_f32 v10, v12, v13
	v_cvt_pk_bf16_f32 v11, v14, v15
	global_store_dwordx2 v[80:81], v[8:9], off offset:2560
	global_store_dwordx2 v[84:85], v[10:11], off offset:2560
	s_nop 0
	v_pk_mul_f32 v[12:13], v[36:37], v[28:29] op_sel_hi:[1,0]
	v_pk_mul_f32 v[14:15], v[38:39], v[28:29] op_sel_hi:[1,0]
	s_nop 0
	v_pk_mul_f32 v[6:7], v[6:7], v[162:163]
	v_pk_mul_f32 v[4:5], v[4:5], v[160:161]
	v_pk_mul_f32 v[10:11], v[14:15], v[162:163]
	v_pk_mul_f32 v[8:9], v[12:13], v[160:161]
	v_cvt_pk_bf16_f32 v4, v4, v5
	v_cvt_pk_bf16_f32 v5, v6, v7
	v_cvt_pk_bf16_f32 v6, v8, v9
	v_cvt_pk_bf16_f32 v7, v10, v11
	global_store_dwordx2 v[80:81], v[4:5], off offset:3072
	global_store_dwordx2 v[84:85], v[6:7], off offset:3072
	s_nop 0
	v_pk_mul_f32 v[8:9], v[32:33], v[28:29] op_sel_hi:[1,0]
	v_pk_mul_f32 v[10:11], v[34:35], v[28:29] op_sel_hi:[1,0]
	s_nop 0
	v_pk_mul_f32 v[2:3], v[2:3], v[166:167]
	v_pk_mul_f32 v[0:1], v[0:1], v[164:165]
	v_pk_mul_f32 v[6:7], v[10:11], v[166:167]
	v_pk_mul_f32 v[4:5], v[8:9], v[164:165]
	v_cvt_pk_bf16_f32 v0, v0, v1
	v_cvt_pk_bf16_f32 v1, v2, v3
	v_cvt_pk_bf16_f32 v2, v4, v5
	v_cvt_pk_bf16_f32 v3, v6, v7
	global_store_dwordx2 v[80:81], v[0:1], off offset:3584
	global_store_dwordx2 v[84:85], v[2:3], off offset:3584
	v_lshl_add_u64 v[80:81], v[80:81], 0, s[30:31]
	s_cbranch_scc0 .LBB0_50
	v_readlane_b32 s0, v254, 41
	s_add_i32 s4, s0, s9

; template <bool OUT_BF16> __device__ __forceinline__ void rms_rows(const float* X, const float* gain, void* out, int gw, int ngw, int lane) {
;     int m = gw;
;     for (; m + ngw < M; m += 2 * ngw) {
;         const f32x4* xr0 = (const f32x4*)(X + (size_t)m * D) + lane; const f32x4* xr1 = (const f32x4*)(X + (size_t)(m + ngw) * D) + lane;
;         f32x4 v0[8], v1[8]; float s0 = 0.f, s1 = 0.f;
; #pragma unroll
;         for (int j = 0; j < 8; ++j) { v0[j] = xr0[64 * j]; v1[j] = xr1[64 * j]; }
.LBB0_790:
	s_cmp_lt_i32 s74, 12
	s_cselect_b64 s[2:3], -1, 0
	s_and_b64 s[0:1], s[2:3], s[0:1]
	s_andn2_b64 vcc, exec, s[0:1]
	v_readlane_b32 s14, v254, 42
	v_readlane_b32 s15, v254, 43
	s_cbranch_vccnz .LBB0_798
	s_add_i32 s0, s68, s14
	s_cmpk_gt_i32 s0, 0x3fff
	v_lshlrev_b32_e32 v56, 4, v188
	v_mbcnt_lo_u32_b32 v72, -1, 0
	s_cbranch_scc1 .LBB0_795
	v_mbcnt_hi_u32_b32 v0, -1, v72
	v_and_b32_e32 v1, 64, v0
	v_add_u32_e32 v1, 64, v1
	v_xor_b32_e32 v2, 1, v0
	v_cmp_lt_i32_e32 vcc, v2, v1
	v_mov_b32_e32 v57, 0
	v_mov_b32_e32 v3, v57
	v_cndmask_b32_e32 v2, v0, v2, vcc
	v_lshlrev_b32_e32 v73, 2, v2
	v_xor_b32_e32 v2, 2, v0
	v_cmp_lt_i32_e32 vcc, v2, v1
	v_mov_b32_e32 v5, v57
	s_add_i32 s1, s66, s67
	v_cndmask_b32_e32 v2, v0, v2, vcc
	v_lshlrev_b32_e32 v74, 2, v2
	v_xor_b32_e32 v2, 4, v0
	v_cmp_lt_i32_e32 vcc, v2, v1
	s_ashr_i32 s69, s68, 31
	s_lshl_b32 s4, s67, 4
	v_cndmask_b32_e32 v2, v0, v2, vcc
	v_lshlrev_b32_e32 v75, 2, v2
	v_xor_b32_e32 v2, 8, v0
	v_cmp_lt_i32_e32 vcc, v2, v1
	v_mov_b32_e32 v7, v57
	s_lshl_b32 s10, s1, 3
	v_cndmask_b32_e32 v2, v0, v2, vcc
	v_lshlrev_b32_e32 v76, 2, v2
	v_xor_b32_e32 v2, 16, v0
	v_cmp_lt_i32_e32 vcc, v2, v1
	s_lshl_b64 s[2:3], s[68:69], 13
	s_add_u32 s2, s88, s2
	v_cndmask_b32_e32 v2, v0, v2, vcc
	v_lshlrev_b32_e32 v77, 2, v2
	v_xor_b32_e32 v2, 32, v0
	v_cmp_lt_i32_e32 vcc, v2, v1
	v_mov_b32_e32 v9, v57
	s_addc_u32 s3, s89, s3
	v_cndmask_b32_e32 v0, v0, v2, vcc
	v_lshlrev_b32_e32 v78, 2, v0
	v_or_b32_e32 v0, 0x100, v188
	v_lshlrev_b32_e32 v2, 4, v0
	v_lshl_add_u64 v[62:63], s[86:87], 0, v[2:3]
	v_or_b32_e32 v2, 0x140, v188
	v_lshlrev_b32_e32 v4, 4, v2
	v_lshl_add_u64 v[64:65], s[86:87], 0, v[4:5]
	v_or_b32_e32 v4, 0x180, v188
	v_lshlrev_b32_e32 v6, 4, v4
	v_lshl_add_u64 v[66:67], s[86:87], 0, v[6:7]
	v_or_b32_e32 v6, 0x1c0, v188
	v_lshlrev_b32_e32 v8, 4, v6
	v_lshl_add_u64 v[68:69], s[86:87], 0, v[8:9]
	v_lshl_add_u64 v[8:9], s[2:3], 0, v[56:57]
	s_mov_b64 s[2:3], 0x1000
	s_ashr_i32 s5, s4, 31
	v_lshl_add_u64 v[58:59], s[88:89], 0, v[56:57]
	v_lshl_add_u64 v[60:61], s[86:87], 0, v[56:57]
	v_lshl_add_u64 v[70:71], v[8:9], 0, s[2:3]
	s_lshl_b64 s[6:7], s[4:5], 13
	s_movk_i32 s5, 0x1000
	v_mov_b32_e32 v57, 0x358637bd
	s_mov_b32 s11, 0xf800000
	v_mov_b32_e32 v79, 0x260
	v_lshlrev_b32_e32 v80, 4, v188
	v_lshlrev_b32_e32 v81, 4, v0
	v_lshlrev_b32_e32 v82, 4, v2
	v_lshlrev_b32_e32 v83, 4, v4
	v_lshlrev_b32_e32 v84, 4, v6
	v_readlane_b32 s12, v254, 40
	global_load_dwordx4 v[140:143], v[60:61], off offset:1024
	global_load_dwordx4 v[144:147], v[60:61], off offset:2048
	global_load_dwordx4 v[148:151], v[60:61], off offset:3072
	global_load_dwordx4 v[152:155], v[62:63], off
	global_load_dwordx4 v[156:159], v[64:65], off
	global_load_dwordx4 v[160:163], v[66:67], off
	global_load_dwordx4 v[164:167], v[68:69], off
.LBB0_793:
	global_load_dwordx4 v[28:31], v[70:71], off offset:-4096
	global_load_dwordx4 v[24:27], v[70:71], off offset:-3072
	global_load_dwordx4 v[20:23], v[70:71], off offset:-2048
	global_load_dwordx4 v[12:15], v[70:71], off
	global_load_dwordx4 v[16:19], v[70:71], off offset:-1024
	global_load_dwordx4 v[8:11], v[70:71], off offset:1024
	global_load_dwordx4 v[0:3], v[70:71], off offset:3072
	global_load_dwordx4 v[4:7], v[70:71], off offset:2048
	s_ashr_i32 s1, s0, 31
	s_lshl_b64 s[0:1], s[0:1], 13
	v_lshl_add_u64 v[32:33], v[58:59], 0, s[0:1]
	global_load_dwordx4 v[86:89], v[60:61], off
	global_load_dwordx4 v[90:93], v[32:33], off
	global_load_dwordx4 v[94:97], v[32:33], off offset:1024
	global_load_dwordx4 v[52:55], v[32:33], off offset:2048
	global_load_dwordx4 v[48:51], v[32:33], off offset:3072
	v_add_co_u32_e32 v98, vcc, s5, v32
	s_add_u32 s8, s88, s0
	s_nop 0
	v_addc_co_u32_e32 v99, vcc, 0, v33, vcc
	global_load_dwordx4 v[44:47], v[98:99], off
	global_load_dwordx4 v[40:43], v[98:99], off offset:1024
	global_load_dwordx4 v[32:35], v[98:99], off offset:3072
	global_load_dwordx4 v[36:39], v[98:99], off offset:2048
	s_addc_u32 s9, s89, s1
	s_add_i32 s68, s68, s4
	s_add_i32 s12, s12, s4
	s_waitcnt vmcnt(16)
	v_mov_b32_e32 v100, v29
	s_waitcnt vmcnt(15)
	v_mov_b32_e32 v101, v25
	v_mov_b32_e32 v104, v31
	v_mov_b32_e32 v105, v27
	v_mov_b32_e32 v98, v28
	v_mov_b32_e32 v99, v24
	v_mov_b32_e32 v102, v30
	v_mov_b32_e32 v103, v26
	s_waitcnt vmcnt(14)
	v_pk_mul_f32 v[106:107], v[22:23], v[22:23]
	v_pk_mul_f32 v[108:109], v[20:21], v[20:21]
	v_pk_mul_f32 v[100:101], v[100:101], v[100:101]
	v_pk_mul_f32 v[104:105], v[104:105], v[104:105]
	s_waitcnt vmcnt(12)
	v_mul_f32_e32 v110, v17, v17
	v_mul_f32_e32 v112, v19, v19
	s_waitcnt vmcnt(11)
	v_pk_mul_f32 v[114:115], v[10:11], v[10:11]
	v_pk_mul_f32 v[116:117], v[8:9], v[8:9]
	v_pk_mov_b32 v[122:123], v[108:109], v[106:107] op_sel:[1,0]
	v_mov_b32_e32 v109, v107
	v_pk_fma_f32 v[98:99], v[98:99], v[98:99], v[100:101]
	v_pk_fma_f32 v[100:101], v[102:103], v[102:103], v[104:105]
	v_mul_f32_e32 v121, v14, v14
	s_waitcnt vmcnt(9)
	v_mul_f32_e32 v118, v5, v5
	v_mul_f32_e32 v120, v7, v7
	v_pk_fma_f32 v[106:107], v[16:17], v[16:17], v[110:111] op_sel_hi:[1,1,0]
	v_pk_fma_f32 v[110:111], v[18:19], v[18:19], v[112:113] op_sel_hi:[1,1,0]
	v_pk_mov_b32 v[112:113], v[116:117], v[114:115] op_sel:[1,0]
	v_mov_b32_e32 v117, v115
	v_pk_add_f32 v[102:103], v[122:123], v[108:109]
	v_pk_add_f32 v[98:99], v[98:99], v[100:101]
	v_mul_f32_e32 v85, v12, v12
	v_mul_f32_e32 v125, v13, v13
	v_mul_f32_e32 v124, v15, v15
	v_mul_f32_e32 v126, v2, v2
	v_mul_f32_e32 v127, v3, v3
	v_pk_fma_f32 v[114:115], v[4:5], v[4:5], v[118:119] op_sel_hi:[1,1,0]
	v_pk_fma_f32 v[118:119], v[6:7], v[6:7], v[120:121] op_sel_hi:[1,1,0]
	v_pk_add_f32 v[104:105], v[112:113], v[116:117]
	s_waitcnt vmcnt(7)
; __device__ __forceinline__ float wave_sum(float v) {
; #pragma unroll
;     for (int o = 1; o < 64; o <<= 1) v += __shfl_xor(v, o);
;     return v;
; }
; template <bool OUT_BF16> __device__ __forceinline__ void rms_rows(const float* X, const float* gain, void* out, int gw, int ngw, int lane) {
;     ...
;         for (int j = 0; j < 8; ++j) { s0 += (v0[j].x * v0[j].x + v0[j].y * v0[j].y) + (v0[j].z * v0[j].z + v0[j].w * v0[j].w); s1 += (v1[j].x * v1[j].x + v1[j].y * v1[j].y) + (v1[j].z * v1[j].z + v1[j].w * v1[j].w); }
;         const float rs0 = 1.0f / sqrtf(wave_sum(s0) * (1.0f / D) + EPS), rs1 = 1.0f / sqrtf(wave_sum(s1) * (1.0f / D) + EPS);
	v_mov_b32_e32 v108, v91
	s_waitcnt vmcnt(6)
	v_mov_b32_e32 v109, v95
	v_mov_b32_e32 v116, v93
	v_mov_b32_e32 v117, v97
	v_pk_add_f32 v[102:103], v[102:103], v[102:103] op_sel:[0,1] op_sel_hi:[1,0]
	v_pk_add_f32 v[98:99], v[98:99], v[98:99] op_sel:[0,1] op_sel_hi:[1,0]
	v_mov_b32_e32 v107, v121
	v_mov_b32_e32 v111, v124
	v_mov_b32_e32 v115, v126
	v_mov_b32_e32 v119, v127
	v_mov_b32_e32 v100, v90
	v_mov_b32_e32 v101, v94
	v_mov_b32_e32 v112, v92
	v_mov_b32_e32 v113, v96
	s_waitcnt vmcnt(5)
	v_pk_mul_f32 v[120:121], v[54:55], v[54:55]
	v_pk_mul_f32 v[122:123], v[52:53], v[52:53]
	v_pk_mul_f32 v[108:109], v[108:109], v[108:109]
	v_pk_mul_f32 v[116:117], v[116:117], v[116:117]
	v_mov_b32_e32 v103, v125
	v_mov_b32_e32 v99, v85
	v_pk_add_f32 v[106:107], v[106:107], v[110:111]
	v_pk_add_f32 v[114:115], v[114:115], v[118:119]
	v_pk_mov_b32 v[118:119], v[122:123], v[120:121] op_sel:[1,0]
	v_mov_b32_e32 v123, v121
	v_pk_fma_f32 v[100:101], v[100:101], v[100:101], v[108:109]
	v_pk_fma_f32 v[108:109], v[112:113], v[112:113], v[116:117]
	v_pk_add_f32 v[98:99], v[98:99], v[102:103]
	s_waitcnt vmcnt(4)
	v_mul_f32_e32 v110, v49, v49
	v_mul_f32_e32 v124, v51, v51
	v_pk_add_f32 v[112:113], v[118:119], v[122:123]
	v_pk_add_f32 v[100:101], v[100:101], v[108:109]
	v_pk_add_f32 v[98:99], v[98:99], v[106:107]
	v_mul_f32_e32 v129, v0, v0
	v_mul_f32_e32 v128, v1, v1
	v_pk_add_f32 v[104:105], v[104:105], v[104:105] op_sel:[0,1] op_sel_hi:[1,0]
	s_waitcnt vmcnt(3)
	v_mul_f32_e32 v131, v44, v44
	v_mul_f32_e32 v132, v45, v45
	v_mul_f32_e32 v133, v46, v46
	v_mul_f32_e32 v134, v47, v47
	v_pk_fma_f32 v[110:111], v[48:49], v[48:49], v[110:111] op_sel_hi:[1,1,0]
	v_pk_fma_f32 v[120:121], v[50:51], v[50:51], v[124:125] op_sel_hi:[1,1,0]
	v_pk_add_f32 v[102:103], v[112:113], v[112:113] op_sel:[0,1] op_sel_hi:[1,0]
	v_pk_add_f32 v[100:101], v[100:101], v[100:101] op_sel:[0,1] op_sel_hi:[1,0]
	v_pk_add_f32 v[98:99], v[98:99], v[98:99] op_sel:[0,1] op_sel_hi:[1,0]
	s_waitcnt vmcnt(2)
	v_pk_mul_f32 v[124:125], v[42:43], v[42:43]
	v_pk_mul_f32 v[126:127], v[40:41], v[40:41]
	v_mov_b32_e32 v105, v128
	v_mov_b32_e32 v111, v133
	v_mov_b32_e32 v121, v134
	v_mov_b32_e32 v103, v132
	v_mov_b32_e32 v101, v131
	v_mov_b32_e32 v99, v129
	v_pk_mov_b32 v[116:117], v[126:127], v[124:125] op_sel:[1,0]
	v_mov_b32_e32 v127, v125
	v_pk_add_f32 v[108:109], v[110:111], v[120:121]
	v_pk_add_f32 v[100:101], v[100:101], v[102:103]
	v_pk_add_f32 v[98:99], v[98:99], v[104:105]
	s_waitcnt vmcnt(0)
	v_mul_f32_e32 v128, v37, v37
	v_mul_f32_e32 v130, v39, v39
	v_pk_add_f32 v[110:111], v[116:117], v[126:127]
	v_pk_add_f32 v[100:101], v[100:101], v[108:109]
	v_pk_add_f32 v[98:99], v[98:99], v[114:115]
	v_mul_f32_e32 v135, v32, v32
	v_mul_f32_e32 v136, v33, v33
	v_mul_f32_e32 v137, v34, v34
	s_waitcnt lgkmcnt(13)
	v_mul_f32_e32 v138, v35, v35
	v_pk_fma_f32 v[118:119], v[36:37], v[36:37], v[128:129] op_sel_hi:[1,1,0]
	v_pk_fma_f32 v[122:123], v[38:39], v[38:39], v[130:131] op_sel_hi:[1,1,0]
	v_pk_add_f32 v[106:107], v[110:111], v[110:111] op_sel:[0,1] op_sel_hi:[1,0]
	v_pk_add_f32 v[100:101], v[100:101], v[100:101] op_sel:[0,1] op_sel_hi:[1,0]
	v_add_f32_e32 v85, v98, v99
	v_mov_b32_e32 v119, v137
	v_mov_b32_e32 v123, v138
	v_mov_b32_e32 v107, v136
	v_mov_b32_e32 v101, v135
	ds_bpermute_b32 v102, v73, v85
	v_pk_add_f32 v[110:111], v[118:119], v[122:123]
	v_pk_add_f32 v[98:99], v[100:101], v[106:107]
	s_waitcnt lgkmcnt(0)
	v_add_f32_e32 v85, v85, v102
	v_pk_add_f32 v[98:99], v[98:99], v[110:111]
	ds_bpermute_b32 v100, v74, v85
	v_add_f32_e32 v98, v98, v99
	ds_bpermute_b32 v99, v73, v98
	s_waitcnt lgkmcnt(1)
	v_add_f32_e32 v85, v85, v100
	ds_bpermute_b32 v100, v75, v85
	s_waitcnt lgkmcnt(1)
	v_add_f32_e32 v98, v98, v99
	ds_bpermute_b32 v99, v74, v98
	s_waitcnt lgkmcnt(1)
	v_add_f32_e32 v85, v85, v100
	ds_bpermute_b32 v100, v76, v85
	s_waitcnt lgkmcnt(1)
	v_add_f32_e32 v98, v98, v99
	ds_bpermute_b32 v99, v75, v98
	s_waitcnt lgkmcnt(1)
	v_add_f32_e32 v85, v85, v100
	ds_bpermute_b32 v100, v77, v85
	s_waitcnt lgkmcnt(1)
	v_add_f32_e32 v98, v98, v99
	ds_bpermute_b32 v99, v76, v98
	s_waitcnt lgkmcnt(1)
	v_add_f32_e32 v85, v85, v100
	ds_bpermute_b32 v100, v78, v85
	s_waitcnt lgkmcnt(1)
	v_add_f32_e32 v98, v98, v99
	ds_bpermute_b32 v99, v77, v98
	s_waitcnt lgkmcnt(1)
	v_add_f32_e32 v85, v85, v100
	v_fmamk_f32 v85, v85, 0x3a000000, v57
	s_waitcnt lgkmcnt(0)
	v_add_f32_e32 v98, v98, v99
	ds_bpermute_b32 v99, v78, v98
	v_mul_f32_e32 v100, 0x4f800000, v85
	v_cmp_gt_f32_e32 vcc, s11, v85
	s_waitcnt lgkmcnt(0)
; __device__ __forceinline__ unsigned pk2(float lo, float hi) { typedef float f2_t __attribute__((ext_vector_type(2))); typedef __bf16 b2_t __attribute__((ext_vector_type(2))); const f2_t v = {lo, hi}; return __builtin_bit_cast(unsigned, __builtin_convertvector(v, b2_t)); }
; template <bool OUT_BF16> __device__ __forceinline__ void rms_rows(const float* X, const float* gain, void* out, int gw, int ngw, int lane) {
;     ...
;         const float rs0 = 1.0f / sqrtf(wave_sum(s0) * (1.0f / D) + EPS), rs1 = 1.0f / sqrtf(wave_sum(s1) * (1.0f / D) + EPS);
; #pragma unroll
;         for (int j = 0; j < 8; ++j) {
;             const f32x4 g = ((const f32x4*)gain)[lane + 64 * j]; const f32x4 o0 = v0[j] * rs0 * g, o1 = v1[j] * rs1 * g;
;             if (OUT_BF16) { v2u w0, w1; w0.x = pk2(o0.x, o0.y); w0.y = pk2(o0.z, o0.w); w1.x = pk2(o1.x, o1.y); w1.y = pk2(o1.z, o1.w);
;                 ((v2u*)((bf16*)out + (size_t)m * D))[lane + 64 * j] = w0; ((v2u*)((bf16*)out + (size_t)(m + ngw) * D))[lane + 64 * j] = w1; }
;             else { ((f32x4*)((float*)out + (size_t)m * D))[lane + 64 * j] = o0; ((f32x4*)((float*)out + (size_t)(m + ngw) * D))[lane + 64 * j] = o1; }
	v_add_f32_e32 v98, v98, v99
	v_cndmask_b32_e32 v85, v85, v100, vcc
	v_sqrt_f32_e32 v99, v85
	v_fmamk_f32 v98, v98, 0x3a000000, v57
	v_mul_f32_e32 v100, 0x4f800000, v98
	v_cmp_gt_f32_e64 s[0:1], s11, v98
	v_add_u32_e32 v101, -1, v99
	v_add_u32_e32 v102, 1, v99
	v_cndmask_b32_e64 v98, v98, v100, s[0:1]
	v_sqrt_f32_e32 v100, v98
	v_fma_f32 v103, -v101, v99, v85
	v_fma_f32 v104, -v102, v99, v85
	v_cmp_ge_f32_e64 s[2:3], 0, v103
	s_nop 1
	v_cndmask_b32_e64 v99, v99, v101, s[2:3]
	v_cmp_lt_f32_e64 s[2:3], 0, v104
	v_add_u32_e32 v101, -1, v100
	v_fma_f32 v104, -v101, v100, v98
	v_cndmask_b32_e64 v99, v99, v102, s[2:3]
	v_add_u32_e32 v102, 1, v100
	v_mul_f32_e32 v103, 0x37800000, v99
	v_fma_f32 v105, -v102, v100, v98
	v_cndmask_b32_e32 v99, v99, v103, vcc
	v_cmp_ge_f32_e32 vcc, 0, v104
	v_cmp_class_f32_e64 s[2:3], v85, v79
	s_nop 0
	v_cndmask_b32_e32 v100, v100, v101, vcc
	v_cmp_lt_f32_e32 vcc, 0, v105
	v_cndmask_b32_e64 v85, v99, v85, s[2:3]
	s_nop 0
	v_cndmask_b32_e32 v99, v100, v102, vcc
	v_div_scale_f32 v100, s[2:3], v85, v85, 1.0
	v_mul_f32_e32 v102, 0x37800000, v99
	v_rcp_f32_e32 v103, v100
	v_cndmask_b32_e64 v99, v99, v102, s[0:1]
	v_cmp_class_f32_e64 s[0:1], v98, v79
	v_div_scale_f32 v101, vcc, 1.0, v85, 1.0
	s_nop 0
	v_cndmask_b32_e64 v99, v99, v98, s[0:1]
	v_div_scale_f32 v102, s[0:1], v99, v99, 1.0
	v_rcp_f32_e32 v105, v102
	v_fma_f32 v98, -v100, v103, 1.0
	v_fmac_f32_e32 v103, v98, v103
	v_mul_f32_e32 v98, v101, v103
	v_fma_f32 v106, -v100, v98, v101
	v_fma_f32 v107, -v102, v105, 1.0
	v_div_scale_f32 v104, s[0:1], 1.0, v99, 1.0
	v_fmac_f32_e32 v98, v106, v103
	v_fmac_f32_e32 v105, v107, v105
	v_fma_f32 v100, -v100, v98, v101
	v_mul_f32_e32 v101, v104, v105
	v_div_fmas_f32 v98, v100, v103, v98
	v_fma_f32 v100, -v102, v101, v104
	v_fmac_f32_e32 v101, v100, v105
	v_div_fixup_f32 v98, v98, v85, 1.0
	v_fma_f32 v85, -v102, v101, v104
	s_mov_b64 vcc, s[0:1]
	v_pk_mul_f32 v[28:29], v[28:29], v[98:99] op_sel_hi:[1,0]
	v_pk_mul_f32 v[30:31], v[30:31], v[98:99] op_sel_hi:[1,0]
	v_div_fmas_f32 v85, v85, v105, v101
	v_pk_mul_f32 v[30:31], v[88:89], v[30:31]
	v_pk_mul_f32 v[28:29], v[86:87], v[28:29]
	v_div_fixup_f32 v100, v85, v99, 1.0
	global_store_dwordx4 v[70:71], v[28:31], off offset:-4096
	v_pk_mul_f32 v[26:27], v[26:27], v[98:99] op_sel_hi:[1,0]
	v_pk_mul_f32 v[24:25], v[24:25], v[98:99] op_sel_hi:[1,0]
	v_pk_mul_f32 v[28:29], v[90:91], v[100:101] op_sel_hi:[1,0]
	v_pk_mul_f32 v[30:31], v[92:93], v[100:101] op_sel_hi:[1,0]
	v_pk_mul_f32 v[28:29], v[86:87], v[28:29]
	v_pk_mul_f32 v[30:31], v[88:89], v[30:31]
	global_store_dwordx4 v80, v[28:31], s[8:9]
	s_nop 0
	v_pk_mul_f32 v[86:87], v[96:97], v[100:101] op_sel_hi:[1,0]
	v_pk_mul_f32 v[88:89], v[94:95], v[100:101] op_sel_hi:[1,0]
	v_pk_mul_f32 v[22:23], v[22:23], v[98:99] op_sel_hi:[1,0]
	v_pk_mul_f32 v[20:21], v[20:21], v[98:99] op_sel_hi:[1,0]
	v_pk_mul_f32 v[18:19], v[18:19], v[98:99] op_sel_hi:[1,0]
	v_pk_mul_f32 v[16:17], v[16:17], v[98:99] op_sel_hi:[1,0]
	v_pk_mul_f32 v[14:15], v[14:15], v[98:99] op_sel_hi:[1,0]
	v_pk_mul_f32 v[12:13], v[12:13], v[98:99] op_sel_hi:[1,0]
	v_pk_mul_f32 v[10:11], v[10:11], v[98:99] op_sel_hi:[1,0]
	v_pk_mul_f32 v[8:9], v[8:9], v[98:99] op_sel_hi:[1,0]
	v_pk_mul_f32 v[6:7], v[6:7], v[98:99] op_sel_hi:[1,0]
	v_pk_mul_f32 v[4:5], v[4:5], v[98:99] op_sel_hi:[1,0]
	v_pk_mul_f32 v[2:3], v[2:3], v[98:99] op_sel_hi:[1,0]
	v_pk_mul_f32 v[0:1], v[0:1], v[98:99] op_sel_hi:[1,0]
	s_add_i32 s0, s68, s14
	s_add_i32 s1, s10, s12
	s_cmpk_gt_i32 s1, 0x3fff
	s_nop 0
	v_pk_mul_f32 v[24:25], v[140:141], v[24:25]
	v_pk_mul_f32 v[26:27], v[142:143], v[26:27]
	v_pk_mul_f32 v[28:29], v[140:141], v[88:89]
	v_pk_mul_f32 v[30:31], v[142:143], v[86:87]
	global_store_dwordx4 v[70:71], v[24:27], off offset:-3072
	global_store_dwordx4 v80, v[28:31], s[8:9] offset:1024
	s_nop 0
	s_nop 0
	v_pk_mul_f32 v[20:21], v[20:21], v[144:145]
	v_pk_mul_f32 v[28:29], v[54:55], v[100:101] op_sel_hi:[1,0]
	v_pk_mul_f32 v[30:31], v[52:53], v[100:101] op_sel_hi:[1,0]
	v_pk_mul_f32 v[22:23], v[22:23], v[146:147]
	v_pk_mul_f32 v[24:25], v[144:145], v[30:31]
	v_pk_mul_f32 v[26:27], v[146:147], v[28:29]
	global_store_dwordx4 v[70:71], v[20:23], off offset:-2048
	global_store_dwordx4 v80, v[24:27], s[8:9] offset:2048
	s_nop 0
	s_nop 0
	v_pk_mul_f32 v[16:17], v[16:17], v[148:149]
	v_pk_mul_f32 v[24:25], v[50:51], v[100:101] op_sel_hi:[1,0]
	v_pk_mul_f32 v[26:27], v[48:49], v[100:101] op_sel_hi:[1,0]
	v_pk_mul_f32 v[18:19], v[18:19], v[150:151]
	v_pk_mul_f32 v[20:21], v[26:27], v[148:149]
	v_pk_mul_f32 v[22:23], v[24:25], v[150:151]
	global_store_dwordx4 v[70:71], v[16:19], off offset:-1024
	global_store_dwordx4 v80, v[20:23], s[8:9] offset:3072
	s_nop 0
	s_nop 0
	v_pk_mul_f32 v[12:13], v[12:13], v[152:153]
	v_pk_mul_f32 v[20:21], v[46:47], v[100:101] op_sel_hi:[1,0]
	v_pk_mul_f32 v[22:23], v[44:45], v[100:101] op_sel_hi:[1,0]
	v_pk_mul_f32 v[14:15], v[14:15], v[154:155]
	v_pk_mul_f32 v[16:17], v[22:23], v[152:153]
	v_pk_mul_f32 v[18:19], v[20:21], v[154:155]
	global_store_dwordx4 v[70:71], v[12:15], off
	global_store_dwordx4 v81, v[16:19], s[8:9]
	s_nop 0
	s_nop 0
	v_pk_mul_f32 v[8:9], v[8:9], v[156:157]
	v_pk_mul_f32 v[16:17], v[42:43], v[100:101] op_sel_hi:[1,0]
	v_pk_mul_f32 v[18:19], v[40:41], v[100:101] op_sel_hi:[1,0]
	v_pk_mul_f32 v[10:11], v[10:11], v[158:159]
	v_pk_mul_f32 v[12:13], v[18:19], v[156:157]
	v_pk_mul_f32 v[14:15], v[16:17], v[158:159]
	global_store_dwordx4 v[70:71], v[8:11], off offset:1024
	global_store_dwordx4 v82, v[12:15], s[8:9]
	s_nop 0
	s_nop 0
	v_pk_mul_f32 v[4:5], v[4:5], v[160:161]
	v_pk_mul_f32 v[12:13], v[38:39], v[100:101] op_sel_hi:[1,0]
	v_pk_mul_f32 v[14:15], v[36:37], v[100:101] op_sel_hi:[1,0]
	v_pk_mul_f32 v[6:7], v[6:7], v[162:163]
	v_pk_mul_f32 v[8:9], v[14:15], v[160:161]
	v_pk_mul_f32 v[10:11], v[12:13], v[162:163]
	global_store_dwordx4 v[70:71], v[4:7], off offset:2048
	global_store_dwordx4 v83, v[8:11], s[8:9]
	s_nop 0
	s_nop 0
	v_pk_mul_f32 v[0:1], v[0:1], v[164:165]
	v_pk_mul_f32 v[8:9], v[34:35], v[100:101] op_sel_hi:[1,0]
	v_pk_mul_f32 v[10:11], v[32:33], v[100:101] op_sel_hi:[1,0]
	v_pk_mul_f32 v[2:3], v[2:3], v[166:167]
	v_pk_mul_f32 v[4:5], v[10:11], v[164:165]
	v_pk_mul_f32 v[6:7], v[8:9], v[166:167]
	global_store_dwordx4 v[70:71], v[0:3], off offset:3072
	global_store_dwordx4 v84, v[4:7], s[8:9]
	v_lshl_add_u64 v[70:71], v[70:71], 0, s[6:7]
	s_cbranch_scc0 .LBB0_793
	v_readlane_b32 s0, v254, 41
	s_add_i32 s68, s0, s12
